# sample attention K tile converted to bf16 before the LDS exchange (each wave converts only its quarter; 4 LDS reads and no per-wave re-conversion)
# speedup vs baseline: 1.0016x; 1.0016x over previous
.Lks_m0:
	v_mbcnt_lo_u32_b32 v76, -1, 0
	v_mbcnt_hi_u32_b32 v76, -1, v76
	v_readlane_b32 s14, v251, 10
	s_lshr_b32 s14, s14, 2
	s_mul_i32 s14, s14, 0x4400
	v_and_b32_e32 v77, 31, v76
	v_lshrrev_b32_e32 v78, 5, v76
	v_mul_u32_u24_e32 v170, 0x90, v77
	v_lshl_add_u32 v170, v78, 4, v170
	v_add_u32_e32 v170, s14, v170
	v_lshrrev_b32_e32 v77, 4, v76
	s_lshl_b32 s15, s81, 3
	v_add_u32_e32 v77, s15, v77
	v_mul_u32_u24_e32 v172, 0x90, v77
	v_and_b32_e32 v77, 15, v76
	v_lshl_add_u32 v172, v77, 3, v172
	v_add_u32_e32 v172, s14, v172
	v_readlane_b32 s34, v251, 10
	v_mbcnt_lo_u32_b32 v250, -1, 0
	v_mbcnt_hi_u32_b32 v250, -1, v250
	s_lshr_b32 s14, s34, 2
	s_lshl_b32 s14, s14, 14
	s_add_i32 s14, s14, 0x12800
	s_bfe_u32 s15, s34, 0x10001
	s_lshl_b32 s15, s15, 12
	s_add_i32 s15, s15, s14
	v_lshrrev_b32_e32 v74, 5, v250
	v_and_b32_e32 v75, 31, v250
	v_lshlrev_b32_e32 v73, 8, v74
	v_lshl_add_u32 v73, v75, 1, v73
	v_add_u32_e32 v73, s15, v73
	v_cvt_pk_bf16_f32 v72, v176, v176
	ds_write_b16 v73, v72 offset:0
	v_cvt_pk_bf16_f32 v72, v179, v179
	ds_write_b16 v73, v72 offset:64
	v_cvt_pk_bf16_f32 v72, v195, v195
	ds_write_b16 v73, v72 offset:128
	v_cvt_pk_bf16_f32 v72, v204, v204
	ds_write_b16 v73, v72 offset:192
	v_cvt_pk_bf16_f32 v72, v219, v219
	ds_write_b16 v73, v72 offset:512
	v_cvt_pk_bf16_f32 v72, v228, v228
	ds_write_b16 v73, v72 offset:576
	v_cvt_pk_bf16_f32 v72, v239, v239
	ds_write_b16 v73, v72 offset:640
	v_cvt_pk_bf16_f32 v72, v242, v242
	ds_write_b16 v73, v72 offset:704
	v_cvt_pk_bf16_f32 v72, v175, v175
	ds_write_b16 v73, v72 offset:1024
	v_cvt_pk_bf16_f32 v72, v178, v178
	ds_write_b16 v73, v72 offset:1088
	v_cvt_pk_bf16_f32 v72, v186, v186
	ds_write_b16 v73, v72 offset:1152
	v_cvt_pk_bf16_f32 v72, v202, v202
	ds_write_b16 v73, v72 offset:1216
	v_cvt_pk_bf16_f32 v72, v218, v218
	ds_write_b16 v73, v72 offset:1536
	v_cvt_pk_bf16_f32 v72, v226, v226
	ds_write_b16 v73, v72 offset:1600
	v_cvt_pk_bf16_f32 v72, v238, v238
	ds_write_b16 v73, v72 offset:1664
	v_cvt_pk_bf16_f32 v72, v241, v241
	ds_write_b16 v73, v72 offset:1728
	v_cvt_pk_bf16_f32 v72, v174, v174
	ds_write_b16 v73, v72 offset:2048
	v_cvt_pk_bf16_f32 v72, v177, v177
	ds_write_b16 v73, v72 offset:2112
	v_cvt_pk_bf16_f32 v72, v184, v184
	ds_write_b16 v73, v72 offset:2176
	v_cvt_pk_bf16_f32 v72, v200, v200
	ds_write_b16 v73, v72 offset:2240
	v_cvt_pk_bf16_f32 v72, v216, v216
	ds_write_b16 v73, v72 offset:2560
	v_cvt_pk_bf16_f32 v72, v224, v224
	ds_write_b16 v73, v72 offset:2624
	v_cvt_pk_bf16_f32 v72, v237, v237
	ds_write_b16 v73, v72 offset:2688
	v_cvt_pk_bf16_f32 v72, v240, v240
	ds_write_b16 v73, v72 offset:2752
	v_cvt_pk_bf16_f32 v72, v173, v173
	ds_write_b16 v73, v72 offset:3072
	v_cvt_pk_bf16_f32 v72, v180, v180
	ds_write_b16 v73, v72 offset:3136
	v_cvt_pk_bf16_f32 v72, v183, v183
	ds_write_b16 v73, v72 offset:3200
	v_cvt_pk_bf16_f32 v72, v207, v207
	ds_write_b16 v73, v72 offset:3264
	v_cvt_pk_bf16_f32 v72, v214, v214
	ds_write_b16 v73, v72 offset:3584
	v_cvt_pk_bf16_f32 v72, v231, v231
	ds_write_b16 v73, v72 offset:3648
	v_cvt_pk_bf16_f32 v72, v236, v236
	ds_write_b16 v73, v72 offset:3712
	v_cvt_pk_bf16_f32 v72, v243, v243
	ds_write_b16 v73, v72 offset:3776
	v_bfe_u32 v76, v250, 4, 1
	v_lshlrev_b32_e32 v76, 5, v76
	v_and_b32_e32 v77, 3, v250
	v_lshl_add_u32 v76, v77, 3, v76
	v_bfe_u32 v77, v250, 2, 2
	v_lshl_add_u32 v77, v74, 2, v77
	v_lshl_add_u32 v249, v77, 6, v76
	v_add_u32_e32 v249, s15, v249
	s_and_b32 s15, s34, 3
	s_lshl_b32 s48, s15, 9
	s_add_i32 s48, s48, s14
	v_lshrrev_b32_e32 v76, 3, v75
	v_lshlrev_b32_e32 v76, 11, v76
	v_lshl_add_u32 v76, v74, 6, v76
	v_and_b32_e32 v77, 7, v250
	v_lshl_add_u32 v248, v77, 3, v76
	v_add_u32_e32 v248, s48, v248
	s_lshl_b32 s15, s15, 15
	v_lshlrev_b32_e32 v76, 12, v74
	v_lshl_add_u32 v250, v75, 4, v76
	v_add_u32_e32 v250, s15, v250
	s_mov_b32 s34, 0x2000
	s_lshl_b32 s81, s81, 15
	s_movk_i32 s32, 0x2200
; __device__ __forceinline__ void sattn_unit(const Args& a, LAS unsigned char* lds, const LAS float* bt, int db, int h, int t, int tid, int wave, int lane) {
;     ...
;     for (int it = 0; it < nf; ++it) {
;         const int key0 = __builtin_amdgcn_readfirstlane((tile0 + it) * 32);
;         bf16x8 kf[4]; bf16x8 vf[2][2];
;         SA_CVT();
;         if (it + 1 < nf) SA_LOAD(key0 + 32);
;         SA_COMPUTE(key0);
.LBB0_295:
	v_cvt_pk_bf16_f32 v64, v64, v65
	v_cvt_pk_bf16_f32 v65, v66, v67
	v_cvt_pk_bf16_f32 v66, v68, v69
	v_cvt_pk_bf16_f32 v67, v70, v71
	ds_write_b64 v172, v[64:65] offset:40960
	ds_write_b64 v172, v[66:67] offset:41536
	s_waitcnt lgkmcnt(0)
	s_barrier
	ds_read_b64_tr_b16 v[72:73], v249
	ds_read_b64_tr_b16 v[74:75], v249 offset:512
	ds_read_b64_tr_b16 v[76:77], v249 offset:1024
	ds_read_b64_tr_b16 v[78:79], v249 offset:1536
	ds_read_b64_tr_b16 v[80:81], v249 offset:2048
	ds_read_b64_tr_b16 v[82:83], v249 offset:2560
	ds_read_b64_tr_b16 v[84:85], v249 offset:3072
	ds_read_b64_tr_b16 v[86:87], v249 offset:3584
	ds_read_b128 v[108:111], v170 offset:40960
	ds_read_b128 v[100:103], v170 offset:40992
	ds_read_b128 v[96:99], v170 offset:41024
	ds_read_b128 v[104:107], v170 offset:41056
	v_add_u32_e32 v170, s32, v170
	v_add_u32_e32 v172, s32, v172
	s_sub_i32 s32, 0, s32
	v_add_u32_e32 v249, s34, v249
	v_add_u32_e32 v248, s34, v248
	s_sub_i32 s34, 0, s34
	s_add_i32 s0, s96, s35
	s_lshl_b32 vcc_lo, s0, 5
	s_add_i32 s35, s35, 1
	s_cmp_ge_u32 s35, s97
	s_cbranch_scc1 .LBB0_297
	s_add_i32 s0, s30, vcc_lo
	s_ashr_i32 s1, s0, 31
	s_lshl_b64 s[0:1], s[0:1], 12
	s_lshl_b32 s14, s5, 2
	s_or_b32 s0, s0, s14
	s_add_u32 s48, s93, s0
	s_addc_u32 s49, s89, s1
	s_add_u32 s48, s48, s81
	s_addc_u32 s49, s49, 0
	s_add_u32 s0, s42, s0
	s_addc_u32 s1, s43, s1
	v_lshl_add_u64 v[64:65], v[112:113], 2, s[48:49]
	v_lshl_add_u64 v[68:69], v[120:121], 2, s[48:49]
	global_load_dwordx4 v[64:67], v[64:65], off
	s_nop 0
	global_load_dwordx4 v[68:71], v[68:69], off
	s_nop 0
	global_load_dwordx4 v[196:199], v250, s[0:1]
	s_add_u32 s14, s0, 0x2000
	s_addc_u32 s15, s1, 0
	global_load_dwordx4 v[200:203], v250, s[14:15]
	s_add_u32 s48, s0, 0x4000
	s_addc_u32 s49, s1, 0
	global_load_dwordx4 v[204:207], v250, s[48:49]
	s_add_u32 s14, s0, 0x6000
	s_addc_u32 s15, s1, 0
	global_load_dwordx4 v[208:211], v250, s[14:15]
.LBB0_297:
	s_waitcnt lgkmcnt(0)
	v_mfma_f32_32x32x16_bf16 v[32:47], v[108:111], v[60:63], 0
	s_cmp_le_i32 vcc_lo, s10
	v_mfma_f32_32x32x16_bf16 v[32:47], v[100:103], v[56:59], v[32:47]
	v_mfma_f32_32x32x16_bf16 v[32:47], v[96:99], v[52:55], v[32:47]
	v_mfma_f32_32x32x16_bf16 v[32:47], v[104:107], v[48:51], v[32:47]
	s_cbranch_scc1 .LBB0_299
	v_add_u32_e32 v96, vcc_lo, v171
	v_med3_i32 v97, v96, 0, v193
	v_lshl_add_u32 v104, v97, 2, s92
	v_add_u32_e32 v97, 1, v96
	v_med3_i32 v97, v97, 0, v193
	v_lshl_add_u32 v105, v97, 2, s92
	v_add_u32_e32 v97, 2, v96
	v_med3_i32 v97, v97, 0, v193
	v_lshl_add_u32 v106, v97, 2, s92
	v_add_u32_e32 v97, 3, v96
	v_med3_i32 v97, v97, 0, v193
	v_lshl_add_u32 v107, v97, 2, s92
	v_add_u32_e32 v97, 8, v96
	v_med3_i32 v97, v97, 0, v193
	v_lshl_add_u32 v108, v97, 2, s92
	v_add_u32_e32 v97, 9, v96
	v_med3_i32 v97, v97, 0, v193
	v_lshl_add_u32 v109, v97, 2, s92
	v_add_u32_e32 v97, 10, v96
	v_med3_i32 v97, v97, 0, v193
	v_lshl_add_u32 v110, v97, 2, s92
	v_add_u32_e32 v97, 11, v96
	v_med3_i32 v97, v97, 0, v193
	v_lshl_add_u32 v111, v97, 2, s92
	v_add_u32_e32 v97, 16, v96
	v_add_u32_e32 v98, 17, v96
	v_add_u32_e32 v99, 18, v96
	v_add_u32_e32 v100, 19, v96
	v_add_u32_e32 v101, 24, v96
	v_add_u32_e32 v102, 25, v96
	v_add_u32_e32 v103, 26, v96
	v_med3_i32 v97, v97, 0, v193
	v_med3_i32 v98, v98, 0, v193
	v_med3_i32 v99, v99, 0, v193
	v_med3_i32 v100, v100, 0, v193
	v_med3_i32 v101, v101, 0, v193
	v_med3_i32 v102, v102, 0, v193
	v_med3_i32 v103, v103, 0, v193
	v_add_u32_e32 v96, 27, v96
	v_lshl_add_u32 v97, v97, 2, s92
	v_lshl_add_u32 v98, v98, 2, s92
	v_lshl_add_u32 v99, v99, 2, s92
	v_lshl_add_u32 v100, v100, 2, s92
	v_lshl_add_u32 v101, v101, 2, s92
	v_lshl_add_u32 v102, v102, 2, s92
	v_lshl_add_u32 v103, v103, 2, s92
	v_med3_i32 v96, v96, 0, v193
	v_lshl_add_u32 v245, v96, 2, s92
	ds_read_b32 v96, v97
	ds_read_b32 v97, v98
	ds_read_b32 v98, v99
	ds_read_b32 v99, v100
	ds_read_b32 v100, v101
	ds_read_b32 v101, v102
	ds_read_b32 v102, v103
	ds_read_b32 v103, v245
	ds_read_b32 v104, v104
	ds_read_b32 v105, v105
	ds_read_b32 v106, v106
	ds_read_b32 v107, v107
	ds_read_b32 v108, v108
	ds_read_b32 v109, v109
	ds_read_b32 v110, v110
	ds_read_b32 v111, v111
	s_waitcnt lgkmcnt(8)
	v_pk_add_f32 v[46:47], v[46:47], v[102:103]
	v_pk_add_f32 v[44:45], v[44:45], v[100:101]
	v_pk_add_f32 v[42:43], v[42:43], v[98:99]
	v_pk_add_f32 v[40:41], v[40:41], v[96:97]
	s_waitcnt lgkmcnt(0)
	v_pk_add_f32 v[38:39], v[38:39], v[110:111]
	v_pk_add_f32 v[36:37], v[36:37], v[108:109]
	v_pk_add_f32 v[34:35], v[34:35], v[106:107]
	v_pk_add_f32 v[32:33], v[32:33], v[104:105]
